# speedup vs baseline: 1.1241x; 1.0164x over previous
.LBB0_398:
	s_andn2_b64 vcc, exec, s[4:5]
	s_cbranch_vccnz .LBB0_434
	v_readlane_b32 s0, v233, 23
	s_cmp_lt_i32 s0, 7
	s_mov_b64 s[4:5], -1
	s_cbranch_scc1 .LBB0_429
	v_readlane_b32 s0, v233, 23
	s_cmp_gt_i32 s0, 7
	s_cbranch_scc0 .LBB0_426
	v_readlane_b32 s0, v235, 11
	v_readlane_b32 s1, v235, 12
	s_andn2_b64 vcc, exec, s[0:1]
	s_cbranch_vccnz .LBB0_425
	v_readlane_b32 s0, v233, 25
	v_readlane_b32 s1, v233, 26
	s_mov_b32 s8, s0
	s_ashr_i32 s9, s0, 31
	s_mul_hi_i32 s5, s0, 0x12000
	s_mul_i32 s4, s0, 0x12000
	s_mul_hi_i32 s7, s0, 0x6000
	s_mul_i32 s6, s0, 0x6000
	v_writelane_b32 v233, s0, 25
	s_mov_b32 s52, s2
	s_nop 0
	v_writelane_b32 v233, s1, 26
	s_lshl_b64 s[0:1], s[8:9], 20
	v_readlane_b32 s8, v234, 38
	v_readlane_b32 s12, v234, 42
	v_readlane_b32 s13, v234, 43
	s_add_u32 s4, s12, s4
	v_readlane_b32 s14, v234, 44
	s_addc_u32 s5, s13, s5
	v_readlane_b32 s15, v234, 45
	s_add_u32 s6, s14, s6
	s_addc_u32 s7, s15, s7
	v_readlane_b32 s9, v234, 39
	s_add_u32 s8, s4, 0x6000
	v_readlane_b32 s10, v234, 40
	v_readlane_b32 s16, v234, 46
	v_readlane_b32 s17, v234, 47
	v_readlane_b32 s18, v234, 48
	v_readlane_b32 s19, v234, 49
	v_readlane_b32 s20, v234, 50
	v_readlane_b32 s21, v234, 51
	v_readlane_b32 s22, v234, 52
	v_readlane_b32 s23, v234, 53
	s_addc_u32 s9, s5, 0
	v_readlane_b32 s11, v234, 41
	s_add_u32 s10, s4, 0xc000
	v_readlane_b32 s12, v236, 33
	s_addc_u32 s11, s5, 0
	v_readlane_b32 s18, v236, 39
	v_readlane_b32 s22, v236, 43
	v_readlane_b32 s19, v236, 40
	v_readlane_b32 s23, v236, 44
	s_add_u32 s22, s18, s0
	s_addc_u32 s23, s19, s1
	v_readlane_b32 s13, v236, 34
	v_readlane_b32 s14, v236, 35
	v_readlane_b32 s15, v236, 36
	v_readlane_b32 s16, v236, 37
	v_readlane_b32 s17, v236, 38
	v_readlane_b32 s20, v236, 41
	v_readlane_b32 s21, v236, 42
	v_readlane_b32 s24, v236, 45
	v_readlane_b32 s25, v236, 46
	v_readlane_b32 s26, v236, 47
	v_readlane_b32 s27, v236, 48
	v_readlane_b32 s0, v236, 0
	s_cmpk_lg_u32 s0, 0x200
	s_cbranch_scc1 .LBB0_404
	s_branch .Lhp_ft

.Lhp_ft:
	v_and_b32_e32 v94, 31, v93
	v_bfe_u32 v95, v93, 5, 1
	v_lshrrev_b32_e32 v96, 6, v93
	s_nop 0
	v_readfirstlane_b32 s0, v96
	s_lshl_b32 s1, s2, 2
	s_add_u32 s0, s0, s1
	s_and_b32 s17, s0, 127
	s_lshl_b32 s17, s17, 5
	s_lshr_b32 s20, s0, 7
	v_add_u32_e32 v96, s17, v94
	v_lshlrev_b32_e32 v96, 2, v96
	v_lshl_add_u32 v97, v95, 19, v96
	v_lshlrev_b32_e32 v98, 8, v94
	v_lshl_add_u32 v98, v95, 7, v98
	v_lshlrev_b32_e32 v96, 2, v94
	v_lshl_add_u32 v99, v95, 16, v96
	v_lshl_add_u32 v100, v95, 12, v96
	v_readlane_b32 s15, v233, 25
	v_readlane_b32 s4, v236, 39
	v_readlane_b32 s5, v236, 40
	s_lshl_b32 s0, s15, 20
	s_add_u32 s4, s4, s0
	s_addc_u32 s5, s5, 0
	v_readlane_b32 s6, v235, 39
	v_readlane_b32 s7, v235, 40
	s_mul_i32 s0, s15, 0x110000
	s_add_u32 s6, s6, s0
	s_addc_u32 s7, s7, 0
	v_readlane_b32 s8, v235, 41
	v_readlane_b32 s9, v235, 42
	s_add_u32 s0, s4, 0x0
	s_addc_u32 s1, s5, 0
	global_load_dword v0, v97, s[0:1]
	s_add_u32 s0, s4, 0x4000
	s_addc_u32 s1, s5, 0
	global_load_dword v1, v97, s[0:1]
	s_add_u32 s0, s4, 0x8000
	s_addc_u32 s1, s5, 0
	global_load_dword v2, v97, s[0:1]
	s_add_u32 s0, s4, 0xc000
	s_addc_u32 s1, s5, 0
	global_load_dword v3, v97, s[0:1]
	s_add_u32 s0, s4, 0x10000
	s_addc_u32 s1, s5, 0
	global_load_dword v4, v97, s[0:1]
	s_add_u32 s0, s4, 0x14000
	s_addc_u32 s1, s5, 0
	global_load_dword v5, v97, s[0:1]
	s_add_u32 s0, s4, 0x18000
	s_addc_u32 s1, s5, 0
	global_load_dword v6, v97, s[0:1]
	s_add_u32 s0, s4, 0x1c000
	s_addc_u32 s1, s5, 0
	global_load_dword v7, v97, s[0:1]
	s_add_u32 s0, s4, 0x20000
	s_addc_u32 s1, s5, 0
	global_load_dword v8, v97, s[0:1]
	s_add_u32 s0, s4, 0x24000
	s_addc_u32 s1, s5, 0
	global_load_dword v9, v97, s[0:1]
	s_add_u32 s0, s4, 0x28000
	s_addc_u32 s1, s5, 0
	global_load_dword v10, v97, s[0:1]
	s_add_u32 s0, s4, 0x2c000
	s_addc_u32 s1, s5, 0
	global_load_dword v11, v97, s[0:1]
	s_add_u32 s0, s4, 0x30000
	s_addc_u32 s1, s5, 0
	global_load_dword v12, v97, s[0:1]
	s_add_u32 s0, s4, 0x34000
	s_addc_u32 s1, s5, 0
	global_load_dword v13, v97, s[0:1]
	s_add_u32 s0, s4, 0x38000
	s_addc_u32 s1, s5, 0
	global_load_dword v14, v97, s[0:1]
	s_add_u32 s0, s4, 0x3c000
	s_addc_u32 s1, s5, 0
	global_load_dword v15, v97, s[0:1]
	s_add_u32 s0, s4, 0x40000
	s_addc_u32 s1, s5, 0
	global_load_dword v16, v97, s[0:1]
	s_add_u32 s0, s4, 0x44000
	s_addc_u32 s1, s5, 0
	global_load_dword v17, v97, s[0:1]
	s_add_u32 s0, s4, 0x48000
	s_addc_u32 s1, s5, 0
	global_load_dword v18, v97, s[0:1]
	s_add_u32 s0, s4, 0x4c000
	s_addc_u32 s1, s5, 0
	global_load_dword v19, v97, s[0:1]
	s_add_u32 s0, s4, 0x50000
	s_addc_u32 s1, s5, 0
	global_load_dword v20, v97, s[0:1]
	s_add_u32 s0, s4, 0x54000
	s_addc_u32 s1, s5, 0
	global_load_dword v21, v97, s[0:1]
	s_add_u32 s0, s4, 0x58000
	s_addc_u32 s1, s5, 0
	global_load_dword v22, v97, s[0:1]
	s_add_u32 s0, s4, 0x5c000
	s_addc_u32 s1, s5, 0
	global_load_dword v23, v97, s[0:1]
	s_add_u32 s0, s4, 0x60000
	s_addc_u32 s1, s5, 0
	global_load_dword v24, v97, s[0:1]
	s_add_u32 s0, s4, 0x64000
	s_addc_u32 s1, s5, 0
	global_load_dword v25, v97, s[0:1]
	s_add_u32 s0, s4, 0x68000
	s_addc_u32 s1, s5, 0
	global_load_dword v26, v97, s[0:1]
	s_add_u32 s0, s4, 0x6c000
	s_addc_u32 s1, s5, 0
	global_load_dword v27, v97, s[0:1]
	s_add_u32 s0, s4, 0x70000
	s_addc_u32 s1, s5, 0
	global_load_dword v28, v97, s[0:1]
	s_add_u32 s0, s4, 0x74000
	s_addc_u32 s1, s5, 0
	global_load_dword v29, v97, s[0:1]
	s_add_u32 s0, s4, 0x78000
	s_addc_u32 s1, s5, 0
	global_load_dword v30, v97, s[0:1]
	s_add_u32 s0, s4, 0x7c000
	s_addc_u32 s1, s5, 0
	global_load_dword v31, v97, s[0:1]
	s_mov_b32 s14, 0
	s_movk_i32 s15, 8
	s_cmpk_lt_u32 s20, 8
	s_addc_u32 s15, s15, 0
.Lhp_ft_tile:
	s_lshl_b32 s0, s20, 3
	s_add_u32 s0, s0, s14
	s_lshl_b32 s12, s0, 5
	s_mov_b32 s13, s12
	s_lshl_b32 s0, s20, 5
	s_add_u32 s1, s0, 0x1000
	s_cmp_eq_u32 s14, 8
	s_cselect_b32 s18, 1, 0
	s_cselect_b32 s12, s0, s12
	s_cselect_b32 s13, s1, s13
	s_lshl_b32 s0, s13, 8
	s_add_u32 s10, s6, s0
	s_addc_u32 s11, s7, 0
	global_load_dwordx4 v[32:35], v98, s[10:11] offset:0
	global_load_dwordx4 v[36:39], v98, s[10:11] offset:16
	global_load_dwordx4 v[40:43], v98, s[10:11] offset:32
	global_load_dwordx4 v[44:47], v98, s[10:11] offset:48
	global_load_dwordx4 v[48:51], v98, s[10:11] offset:64
	global_load_dwordx4 v[52:55], v98, s[10:11] offset:80
	global_load_dwordx4 v[56:59], v98, s[10:11] offset:96
	global_load_dwordx4 v[60:63], v98, s[10:11] offset:112
	s_waitcnt vmcnt(0)
	v_mfma_f32_32x32x2_f32 v[64:79], v0, v32, 0
	v_mfma_f32_32x32x2_f32 v[64:79], v1, v33, v[64:79]
	v_mfma_f32_32x32x2_f32 v[64:79], v2, v34, v[64:79]
	v_mfma_f32_32x32x2_f32 v[64:79], v3, v35, v[64:79]
	v_mfma_f32_32x32x2_f32 v[64:79], v4, v36, v[64:79]
	v_mfma_f32_32x32x2_f32 v[64:79], v5, v37, v[64:79]
	v_mfma_f32_32x32x2_f32 v[64:79], v6, v38, v[64:79]
	v_mfma_f32_32x32x2_f32 v[64:79], v7, v39, v[64:79]
	v_mfma_f32_32x32x2_f32 v[64:79], v8, v40, v[64:79]
	v_mfma_f32_32x32x2_f32 v[64:79], v9, v41, v[64:79]
	v_mfma_f32_32x32x2_f32 v[64:79], v10, v42, v[64:79]
	v_mfma_f32_32x32x2_f32 v[64:79], v11, v43, v[64:79]
	v_mfma_f32_32x32x2_f32 v[64:79], v12, v44, v[64:79]
	v_mfma_f32_32x32x2_f32 v[64:79], v13, v45, v[64:79]
	v_mfma_f32_32x32x2_f32 v[64:79], v14, v46, v[64:79]
	v_mfma_f32_32x32x2_f32 v[64:79], v15, v47, v[64:79]
	v_mfma_f32_32x32x2_f32 v[64:79], v16, v48, v[64:79]
	v_mfma_f32_32x32x2_f32 v[64:79], v17, v49, v[64:79]
	v_mfma_f32_32x32x2_f32 v[64:79], v18, v50, v[64:79]
	v_mfma_f32_32x32x2_f32 v[64:79], v19, v51, v[64:79]
	v_mfma_f32_32x32x2_f32 v[64:79], v20, v52, v[64:79]
	v_mfma_f32_32x32x2_f32 v[64:79], v21, v53, v[64:79]
	v_mfma_f32_32x32x2_f32 v[64:79], v22, v54, v[64:79]
	v_mfma_f32_32x32x2_f32 v[64:79], v23, v55, v[64:79]
	v_mfma_f32_32x32x2_f32 v[64:79], v24, v56, v[64:79]
	v_mfma_f32_32x32x2_f32 v[64:79], v25, v57, v[64:79]
	v_mfma_f32_32x32x2_f32 v[64:79], v26, v58, v[64:79]
	v_mfma_f32_32x32x2_f32 v[64:79], v27, v59, v[64:79]
	v_mfma_f32_32x32x2_f32 v[64:79], v28, v60, v[64:79]
	v_mfma_f32_32x32x2_f32 v[64:79], v29, v61, v[64:79]
	v_mfma_f32_32x32x2_f32 v[64:79], v30, v62, v[64:79]
	v_mfma_f32_32x32x2_f32 v[64:79], v31, v63, v[64:79]
	s_nop 15
	s_nop 3
	s_cmp_lg_u32 s18, 0
	s_cbranch_scc1 .Lhp_ft_ctx
	s_lshl_b32 s0, s17, 12
	s_add_u32 s0, s0, s12
	s_lshl_b32 s0, s0, 2
	s_add_u32 s10, s8, s0
	s_addc_u32 s11, s9, 0
	s_add_u32 s0, s10, 0x0
	s_addc_u32 s1, s11, 0
	global_store_dword v99, v64, s[0:1]
	s_add_u32 s0, s10, 0x4000
	s_addc_u32 s1, s11, 0
	global_store_dword v99, v65, s[0:1]
	s_add_u32 s0, s10, 0x8000
	s_addc_u32 s1, s11, 0
	global_store_dword v99, v66, s[0:1]
	s_add_u32 s0, s10, 0xc000
	s_addc_u32 s1, s11, 0
	global_store_dword v99, v67, s[0:1]
	s_add_u32 s0, s10, 0x20000
	s_addc_u32 s1, s11, 0
	global_store_dword v99, v68, s[0:1]
	s_add_u32 s0, s10, 0x24000
	s_addc_u32 s1, s11, 0
	global_store_dword v99, v69, s[0:1]
	s_add_u32 s0, s10, 0x28000
	s_addc_u32 s1, s11, 0
	global_store_dword v99, v70, s[0:1]
	s_add_u32 s0, s10, 0x2c000
	s_addc_u32 s1, s11, 0
	global_store_dword v99, v71, s[0:1]
	s_add_u32 s0, s10, 0x40000
	s_addc_u32 s1, s11, 0
	global_store_dword v99, v72, s[0:1]
	s_add_u32 s0, s10, 0x44000
	s_addc_u32 s1, s11, 0
	global_store_dword v99, v73, s[0:1]
	s_add_u32 s0, s10, 0x48000
	s_addc_u32 s1, s11, 0
	global_store_dword v99, v74, s[0:1]
	s_add_u32 s0, s10, 0x4c000
	s_addc_u32 s1, s11, 0
	global_store_dword v99, v75, s[0:1]
	s_add_u32 s0, s10, 0x60000
	s_addc_u32 s1, s11, 0
	global_store_dword v99, v76, s[0:1]
	s_add_u32 s0, s10, 0x64000
	s_addc_u32 s1, s11, 0
	global_store_dword v99, v77, s[0:1]
	s_add_u32 s0, s10, 0x68000
	s_addc_u32 s1, s11, 0
	global_store_dword v99, v78, s[0:1]
	s_add_u32 s0, s10, 0x6c000
	s_addc_u32 s1, s11, 0
	global_store_dword v99, v79, s[0:1]
	s_branch .Lhp_ft_next
.Lhp_ft_ctx:
	s_lshl_b32 s0, s17, 8
	s_add_u32 s0, s0, s12
	s_lshl_b32 s0, s0, 2
	s_add_u32 s0, s0, 0x4000000
	s_add_u32 s10, s8, s0
	s_addc_u32 s11, s9, 0
	s_add_u32 s0, s10, 0x0
	s_addc_u32 s1, s11, 0
	global_store_dword v100, v64, s[0:1]
	s_add_u32 s0, s10, 0x400
	s_addc_u32 s1, s11, 0
	global_store_dword v100, v65, s[0:1]
	s_add_u32 s0, s10, 0x800
	s_addc_u32 s1, s11, 0
	global_store_dword v100, v66, s[0:1]
	s_add_u32 s0, s10, 0xc00
	s_addc_u32 s1, s11, 0
	global_store_dword v100, v67, s[0:1]
	s_add_u32 s0, s10, 0x2000
	s_addc_u32 s1, s11, 0
	global_store_dword v100, v68, s[0:1]
	s_add_u32 s0, s10, 0x2400
	s_addc_u32 s1, s11, 0
	global_store_dword v100, v69, s[0:1]
	s_add_u32 s0, s10, 0x2800
	s_addc_u32 s1, s11, 0
	global_store_dword v100, v70, s[0:1]
	s_add_u32 s0, s10, 0x2c00
	s_addc_u32 s1, s11, 0
	global_store_dword v100, v71, s[0:1]
	s_add_u32 s0, s10, 0x4000
	s_addc_u32 s1, s11, 0
	global_store_dword v100, v72, s[0:1]
	s_add_u32 s0, s10, 0x4400
	s_addc_u32 s1, s11, 0
	global_store_dword v100, v73, s[0:1]
	s_add_u32 s0, s10, 0x4800
	s_addc_u32 s1, s11, 0
	global_store_dword v100, v74, s[0:1]
	s_add_u32 s0, s10, 0x4c00
	s_addc_u32 s1, s11, 0
	global_store_dword v100, v75, s[0:1]
	s_add_u32 s0, s10, 0x6000
	s_addc_u32 s1, s11, 0
	global_store_dword v100, v76, s[0:1]
	s_add_u32 s0, s10, 0x6400
	s_addc_u32 s1, s11, 0
	global_store_dword v100, v77, s[0:1]
	s_add_u32 s0, s10, 0x6800
	s_addc_u32 s1, s11, 0
	global_store_dword v100, v78, s[0:1]
	s_add_u32 s0, s10, 0x6c00
	s_addc_u32 s1, s11, 0
	global_store_dword v100, v79, s[0:1]
.Lhp_ft_next:
	s_add_u32 s14, s14, 1
	s_cmp_lt_u32 s14, s15
	s_cbranch_scc1 .Lhp_ft_tile
	s_mov_b32 s16, 0
.Lhp_entry:
	s_waitcnt vmcnt(0) lgkmcnt(0)
	s_barrier
	v_and_b32_e32 v164, 15, v93
	v_lshrrev_b32_e32 v165, 4, v93
	v_cmp_eq_u32_e64 s[10:11], 0, v165
	v_cmp_eq_u32_e64 s[12:13], 15, v165
	s_and_b32 s17, s2, 15
	s_lshl_b32 s17, s17, 7
	v_lshl_add_u32 v232, v164, 3, s17
	v_lshlrev_b32_e32 v163, 2, v232
	v_lshlrev_b32_e32 v232, 1, v232
	v_lshlrev_b32_e32 v118, 16, v165
	v_add_u32_e32 v118, v118, v232
	v_add_u32_e32 v119, 0x4000, v118
	v_add_u32_e32 v120, 0x8000, v118
	v_add_u32_e32 v121, 0xc000, v118
	v_add_u32_e32 v122, 0x10000, v118
	v_add_u32_e32 v123, 0x14000, v118
	v_mul_u32_u24_e32 v212, 1152, v164
	v_lshl_add_u32 v212, v165, 3, v212
	v_lshrrev_b32_e32 v232, 1, v93
	v_and_b32_e32 v89, 1, v93
	v_lshlrev_b32_e32 v89, 6, v89
	v_mul_u32_u24_e32 v213, 144, v232
	v_add_u32_e32 v213, v213, v89
	v_lshl_add_u32 v214, v232, 9, v89
	v_lshl_add_u32 v215, v232, 13, v89
	v_readlane_b32 s15, v233, 25
	v_readlane_b32 s4, v234, 42
	v_readlane_b32 s5, v234, 43
	s_mul_i32 s0, s15, 0x12000
	s_add_u32 s4, s4, s0
	s_addc_u32 s5, s5, 0
	v_readlane_b32 s6, v234, 44
	v_readlane_b32 s7, v234, 45
	s_mul_i32 s0, s15, 0x6000
	s_add_u32 s6, s6, s0
	s_addc_u32 s7, s7, 0
	s_add_u32 s0, s4, 0x2000
	s_addc_u32 s1, s5, 0
	global_load_dwordx4 v[0:3], v163, s[0:1]
	global_load_dwordx4 v[4:7], v163, s[0:1] offset:16
	s_add_u32 s0, s4, 0x8000
	s_addc_u32 s1, s5, 0
	global_load_dwordx4 v[8:11], v163, s[0:1]
	global_load_dwordx4 v[12:15], v163, s[0:1] offset:16
	s_add_u32 s0, s4, 0xe000
	s_addc_u32 s1, s5, 0
	global_load_dwordx4 v[16:19], v163, s[0:1]
	global_load_dwordx4 v[20:23], v163, s[0:1] offset:16
	s_add_u32 s0, s6, 0x2000
	s_addc_u32 s1, s7, 0
	global_load_dwordx4 v[24:27], v163, s[0:1]
	global_load_dwordx4 v[28:31], v163, s[0:1] offset:16
	s_add_u32 s0, s4, 0x4000
	s_addc_u32 s1, s5, 0
	global_load_dwordx4 v[32:35], v163, s[0:1]
	global_load_dwordx4 v[36:39], v163, s[0:1] offset:16
	s_add_u32 s0, s4, 0xa000
	s_addc_u32 s1, s5, 0
	global_load_dwordx4 v[40:43], v163, s[0:1]
	global_load_dwordx4 v[44:47], v163, s[0:1] offset:16
	s_add_u32 s0, s4, 0x10000
	s_addc_u32 s1, s5, 0
	global_load_dwordx4 v[48:51], v163, s[0:1]
	global_load_dwordx4 v[52:55], v163, s[0:1] offset:16
	s_add_u32 s0, s6, 0x4000
	s_addc_u32 s1, s7, 0
	global_load_dwordx4 v[56:59], v163, s[0:1]
	global_load_dwordx4 v[60:63], v163, s[0:1] offset:16
	s_mov_b32 s14, 0
	s_lshr_b32 s0, s2, 4
	s_lshl_b32 s1, s14, 5
	s_add_u32 s0, s0, s1
	s_lshl_b32 s15, s0, 6
	v_readlane_b32 s4, v236, 53
	v_readlane_b32 s5, v236, 54
	s_lshl_b32 s0, s15, 14
	s_add_u32 s4, s4, s0
	s_addc_u32 s5, s5, 0
	s_sub_u32 s4, s4, 0x3000
	s_subb_u32 s5, s5, 0
	s_add_u32 s6, s4, 0x1000
	s_addc_u32 s7, s5, 0
	s_and_b32 s17, s2, 15
	s_lshl_b32 s17, s17, 7
	v_readlane_b32 s18, v235, 35
	v_readlane_b32 s19, v235, 36
	s_cmpk_lt_u32 s15, 0x1000
	s_cbranch_scc0 .Lhp_lat_i1
	s_lshr_b32 s0, s15, 8
	s_lshl_b32 s0, s0, 11
	s_add_u32 s0, s0, s17
	s_lshl_b32 s0, s0, 8
	s_and_b32 s1, s15, 255
	s_add_u32 s0, s0, s1
	s_lshl_b32 s0, s0, 1
	s_cmp_eq_u32 s1, 0
	s_cselect_b32 s22, 1, 0
	s_cmp_eq_u32 s1, 192
	s_cselect_b32 s23, 1, 0
	s_mov_b32 s25, 0
	s_branch .Lhp_latd_i1
.Lhp_lat_i1:
	s_sub_u32 s1, s15, 0x1000
	s_lshr_b32 s0, s1, 12
	s_lshl_b32 s0, s0, 11
	s_add_u32 s0, s0, s17
	s_lshl_b32 s0, s0, 12
	s_and_b32 s1, s1, 4095
	s_add_u32 s0, s0, s1
	s_lshl_b32 s0, s0, 1
	s_add_u32 s0, s0, 0x1000000
	s_cmp_eq_u32 s1, 0
	s_cselect_b32 s22, 1, 0
	s_cmp_eq_u32 s1, 4032
	s_cselect_b32 s23, 1, 0
	s_mov_b32 s25, 1
.Lhp_latd_i1:
	s_add_u32 s18, s18, s0
	s_addc_u32 s19, s19, 0
	s_cmp_lg_u32 s22, 0
	s_cselect_b64 s[0:1], s[10:11], 0
	v_cndmask_b32_e64 v124, v118, v119, s[0:1]
	s_cmp_lg_u32 s23, 0
	s_cselect_b64 s[0:1], s[12:13], 0
	v_cndmask_b32_e64 v125, v123, v122, s[0:1]
	global_load_dwordx4 v[64:67], v124, s[4:5]
	global_load_dwordx4 v[94:97], v124, s[6:7]
	global_load_dwordx4 v[68:71], v119, s[4:5]
	global_load_dwordx4 v[98:101], v119, s[6:7]
	global_load_dwordx4 v[72:75], v120, s[4:5]
	global_load_dwordx4 v[102:105], v120, s[6:7]
	global_load_dwordx4 v[76:79], v121, s[4:5]
	global_load_dwordx4 v[106:109], v121, s[6:7]
	global_load_dwordx4 v[80:83], v122, s[4:5]
	global_load_dwordx4 v[110:113], v122, s[6:7]
	global_load_dwordx4 v[84:87], v125, s[4:5]
	global_load_dwordx4 v[114:117], v125, s[6:7]
	s_waitcnt vmcnt(0)
.Lhp_item:
	s_mov_b32 s20, s22
	s_mov_b32 s21, s23
	s_mov_b64 s[8:9], s[18:19]
	s_mov_b32 s24, s25
	s_waitcnt vmcnt(4)
	s_cmp_lg_u32 s20, 0
	s_cselect_b64 s[0:1], s[10:11], 0
	v_cndmask_b32_e64 v64, v64, 0, s[0:1]
	v_cndmask_b32_e64 v94, v94, 0, s[0:1]
	v_cndmask_b32_e64 v65, v65, 0, s[0:1]
	v_cndmask_b32_e64 v95, v95, 0, s[0:1]
	v_cndmask_b32_e64 v66, v66, 0, s[0:1]
	v_cndmask_b32_e64 v96, v96, 0, s[0:1]
	v_cndmask_b32_e64 v67, v67, 0, s[0:1]
	v_cndmask_b32_e64 v97, v97, 0, s[0:1]
	s_cmp_lg_u32 s21, 0
	s_cselect_b64 s[0:1], s[12:13], 0
	v_cndmask_b32_e64 v84, v84, 0, s[0:1]
	v_cndmask_b32_e64 v114, v114, 0, s[0:1]
	v_cndmask_b32_e64 v85, v85, 0, s[0:1]
	v_cndmask_b32_e64 v115, v115, 0, s[0:1]
	v_cndmask_b32_e64 v86, v86, 0, s[0:1]
	v_cndmask_b32_e64 v116, v116, 0, s[0:1]
	v_cndmask_b32_e64 v87, v87, 0, s[0:1]
	v_cndmask_b32_e64 v117, v117, 0, s[0:1]
	v_mov_b32_e32 v232, 0xffff0000
	v_lshlrev_b32_e32 v126, 16, v64
	v_and_b32_e32 v127, v232, v64
	v_lshlrev_b32_e32 v138, 16, v94
	v_and_b32_e32 v139, v232, v94
	v_lshlrev_b32_e32 v128, 16, v68
	v_and_b32_e32 v129, v232, v68
	v_lshlrev_b32_e32 v140, 16, v98
	v_and_b32_e32 v141, v232, v98
	v_lshlrev_b32_e32 v130, 16, v72
	v_and_b32_e32 v131, v232, v72
	v_lshlrev_b32_e32 v142, 16, v102
	v_and_b32_e32 v143, v232, v102
	v_lshlrev_b32_e32 v132, 16, v76
	v_and_b32_e32 v133, v232, v76
	v_lshlrev_b32_e32 v144, 16, v106
	v_and_b32_e32 v145, v232, v106
	v_lshlrev_b32_e32 v134, 16, v80
	v_and_b32_e32 v135, v232, v80
	v_lshlrev_b32_e32 v146, 16, v110
	v_and_b32_e32 v147, v232, v110
	v_lshlrev_b32_e32 v136, 16, v84
	v_and_b32_e32 v137, v232, v84
	v_lshlrev_b32_e32 v148, 16, v114
	v_and_b32_e32 v149, v232, v114
	v_pk_mul_f32 v[150:151], v[126:127], v[0:1]
	v_pk_mul_f32 v[152:153], v[138:139], v[32:33]
	v_pk_fma_f32 v[150:151], v[128:129], v[8:9], v[150:151]
	v_pk_fma_f32 v[152:153], v[140:141], v[40:41], v[152:153]
	v_pk_fma_f32 v[150:151], v[130:131], v[16:17], v[150:151]
	v_pk_fma_f32 v[152:153], v[142:143], v[48:49], v[152:153]
	v_pk_add_f32 v[150:151], v[150:151], v[24:25]
	v_pk_add_f32 v[152:153], v[152:153], v[56:57]
	v_pk_mul_f32 v[154:155], v[150:151], v[152:153]
	v_pk_mul_f32 v[150:151], v[128:129], v[0:1]
	v_pk_mul_f32 v[152:153], v[140:141], v[32:33]
	v_pk_fma_f32 v[150:151], v[130:131], v[8:9], v[150:151]
	v_pk_fma_f32 v[152:153], v[142:143], v[40:41], v[152:153]
	v_pk_fma_f32 v[150:151], v[132:133], v[16:17], v[150:151]
	v_pk_fma_f32 v[152:153], v[144:145], v[48:49], v[152:153]
	v_pk_add_f32 v[150:151], v[150:151], v[24:25]
	v_pk_add_f32 v[152:153], v[152:153], v[56:57]
	v_pk_mul_f32 v[156:157], v[150:151], v[152:153]
	v_pk_mul_f32 v[150:151], v[130:131], v[0:1]
	v_pk_mul_f32 v[152:153], v[142:143], v[32:33]
	v_pk_fma_f32 v[150:151], v[132:133], v[8:9], v[150:151]
	v_pk_fma_f32 v[152:153], v[144:145], v[40:41], v[152:153]
	v_pk_fma_f32 v[150:151], v[134:135], v[16:17], v[150:151]
	v_pk_fma_f32 v[152:153], v[146:147], v[48:49], v[152:153]
	v_pk_add_f32 v[150:151], v[150:151], v[24:25]
	v_pk_add_f32 v[152:153], v[152:153], v[56:57]
	v_pk_mul_f32 v[158:159], v[150:151], v[152:153]
	v_pk_mul_f32 v[150:151], v[132:133], v[0:1]
	v_pk_mul_f32 v[152:153], v[144:145], v[32:33]
	v_pk_fma_f32 v[150:151], v[134:135], v[8:9], v[150:151]
	v_pk_fma_f32 v[152:153], v[146:147], v[40:41], v[152:153]
	v_pk_fma_f32 v[150:151], v[136:137], v[16:17], v[150:151]
	v_pk_fma_f32 v[152:153], v[148:149], v[48:49], v[152:153]
	v_pk_add_f32 v[150:151], v[150:151], v[24:25]
	v_pk_add_f32 v[152:153], v[152:153], v[56:57]
	v_pk_mul_f32 v[160:161], v[150:151], v[152:153]
	v_cvt_pk_bf16_f32 v196, v154, v156
	v_cvt_pk_bf16_f32 v197, v158, v160
	v_cvt_pk_bf16_f32 v198, v155, v157
	v_cvt_pk_bf16_f32 v199, v159, v161
	v_lshlrev_b32_e32 v126, 16, v65
	v_and_b32_e32 v127, v232, v65
	v_lshlrev_b32_e32 v138, 16, v95
	v_and_b32_e32 v139, v232, v95
	v_lshlrev_b32_e32 v128, 16, v69
	v_and_b32_e32 v129, v232, v69
	v_lshlrev_b32_e32 v140, 16, v99
	v_and_b32_e32 v141, v232, v99
	v_lshlrev_b32_e32 v130, 16, v73
	v_and_b32_e32 v131, v232, v73
	v_lshlrev_b32_e32 v142, 16, v103
	v_and_b32_e32 v143, v232, v103
	v_lshlrev_b32_e32 v132, 16, v77
	v_and_b32_e32 v133, v232, v77
	v_lshlrev_b32_e32 v144, 16, v107
	v_and_b32_e32 v145, v232, v107
	v_lshlrev_b32_e32 v134, 16, v81
	v_and_b32_e32 v135, v232, v81
	v_lshlrev_b32_e32 v146, 16, v111
	v_and_b32_e32 v147, v232, v111
	v_lshlrev_b32_e32 v136, 16, v85
	v_and_b32_e32 v137, v232, v85
	v_lshlrev_b32_e32 v148, 16, v115
	v_and_b32_e32 v149, v232, v115
	v_pk_mul_f32 v[150:151], v[126:127], v[2:3]
	v_pk_mul_f32 v[152:153], v[138:139], v[34:35]
	v_pk_fma_f32 v[150:151], v[128:129], v[10:11], v[150:151]
	v_pk_fma_f32 v[152:153], v[140:141], v[42:43], v[152:153]
	v_pk_fma_f32 v[150:151], v[130:131], v[18:19], v[150:151]
	v_pk_fma_f32 v[152:153], v[142:143], v[50:51], v[152:153]
	v_pk_add_f32 v[150:151], v[150:151], v[26:27]
	v_pk_add_f32 v[152:153], v[152:153], v[58:59]
	v_pk_mul_f32 v[154:155], v[150:151], v[152:153]
	v_pk_mul_f32 v[150:151], v[128:129], v[2:3]
	v_pk_mul_f32 v[152:153], v[140:141], v[34:35]
	v_pk_fma_f32 v[150:151], v[130:131], v[10:11], v[150:151]
	v_pk_fma_f32 v[152:153], v[142:143], v[42:43], v[152:153]
	v_pk_fma_f32 v[150:151], v[132:133], v[18:19], v[150:151]
	v_pk_fma_f32 v[152:153], v[144:145], v[50:51], v[152:153]
	v_pk_add_f32 v[150:151], v[150:151], v[26:27]
	v_pk_add_f32 v[152:153], v[152:153], v[58:59]
	v_pk_mul_f32 v[156:157], v[150:151], v[152:153]
	v_pk_mul_f32 v[150:151], v[130:131], v[2:3]
	v_pk_mul_f32 v[152:153], v[142:143], v[34:35]
	v_pk_fma_f32 v[150:151], v[132:133], v[10:11], v[150:151]
	v_pk_fma_f32 v[152:153], v[144:145], v[42:43], v[152:153]
	v_pk_fma_f32 v[150:151], v[134:135], v[18:19], v[150:151]
	v_pk_fma_f32 v[152:153], v[146:147], v[50:51], v[152:153]
	v_pk_add_f32 v[150:151], v[150:151], v[26:27]
	v_pk_add_f32 v[152:153], v[152:153], v[58:59]
	v_pk_mul_f32 v[158:159], v[150:151], v[152:153]
	v_pk_mul_f32 v[150:151], v[132:133], v[2:3]
	v_pk_mul_f32 v[152:153], v[144:145], v[34:35]
	v_pk_fma_f32 v[150:151], v[134:135], v[10:11], v[150:151]
	v_pk_fma_f32 v[152:153], v[146:147], v[42:43], v[152:153]
	v_pk_fma_f32 v[150:151], v[136:137], v[18:19], v[150:151]
	v_pk_fma_f32 v[152:153], v[148:149], v[50:51], v[152:153]
	v_pk_add_f32 v[150:151], v[150:151], v[26:27]
	v_pk_add_f32 v[152:153], v[152:153], v[58:59]
	v_pk_mul_f32 v[160:161], v[150:151], v[152:153]
	v_cvt_pk_bf16_f32 v200, v154, v156
	v_cvt_pk_bf16_f32 v201, v158, v160
	v_cvt_pk_bf16_f32 v202, v155, v157
	v_cvt_pk_bf16_f32 v203, v159, v161
	v_lshlrev_b32_e32 v126, 16, v66
	v_and_b32_e32 v127, v232, v66
	v_lshlrev_b32_e32 v138, 16, v96
	v_and_b32_e32 v139, v232, v96
	v_lshlrev_b32_e32 v128, 16, v70
	v_and_b32_e32 v129, v232, v70
	v_lshlrev_b32_e32 v140, 16, v100
	v_and_b32_e32 v141, v232, v100
	v_lshlrev_b32_e32 v130, 16, v74
	v_and_b32_e32 v131, v232, v74
	v_lshlrev_b32_e32 v142, 16, v104
	v_and_b32_e32 v143, v232, v104
	v_lshlrev_b32_e32 v132, 16, v78
	v_and_b32_e32 v133, v232, v78
	v_lshlrev_b32_e32 v144, 16, v108
	v_and_b32_e32 v145, v232, v108
	v_lshlrev_b32_e32 v134, 16, v82
	v_and_b32_e32 v135, v232, v82
	v_lshlrev_b32_e32 v146, 16, v112
	v_and_b32_e32 v147, v232, v112
	v_lshlrev_b32_e32 v136, 16, v86
	v_and_b32_e32 v137, v232, v86
	v_lshlrev_b32_e32 v148, 16, v116
	v_and_b32_e32 v149, v232, v116
	v_pk_mul_f32 v[150:151], v[126:127], v[4:5]
	v_pk_mul_f32 v[152:153], v[138:139], v[36:37]
	v_pk_fma_f32 v[150:151], v[128:129], v[12:13], v[150:151]
	v_pk_fma_f32 v[152:153], v[140:141], v[44:45], v[152:153]
	v_pk_fma_f32 v[150:151], v[130:131], v[20:21], v[150:151]
	v_pk_fma_f32 v[152:153], v[142:143], v[52:53], v[152:153]
	v_pk_add_f32 v[150:151], v[150:151], v[28:29]
	v_pk_add_f32 v[152:153], v[152:153], v[60:61]
	v_pk_mul_f32 v[154:155], v[150:151], v[152:153]
	v_pk_mul_f32 v[150:151], v[128:129], v[4:5]
	v_pk_mul_f32 v[152:153], v[140:141], v[36:37]
	v_pk_fma_f32 v[150:151], v[130:131], v[12:13], v[150:151]
	v_pk_fma_f32 v[152:153], v[142:143], v[44:45], v[152:153]
	v_pk_fma_f32 v[150:151], v[132:133], v[20:21], v[150:151]
	v_pk_fma_f32 v[152:153], v[144:145], v[52:53], v[152:153]
	v_pk_add_f32 v[150:151], v[150:151], v[28:29]
	v_pk_add_f32 v[152:153], v[152:153], v[60:61]
	v_pk_mul_f32 v[156:157], v[150:151], v[152:153]
	v_pk_mul_f32 v[150:151], v[130:131], v[4:5]
	v_pk_mul_f32 v[152:153], v[142:143], v[36:37]
	v_pk_fma_f32 v[150:151], v[132:133], v[12:13], v[150:151]
	v_pk_fma_f32 v[152:153], v[144:145], v[44:45], v[152:153]
	v_pk_fma_f32 v[150:151], v[134:135], v[20:21], v[150:151]
	v_pk_fma_f32 v[152:153], v[146:147], v[52:53], v[152:153]
	v_pk_add_f32 v[150:151], v[150:151], v[28:29]
	v_pk_add_f32 v[152:153], v[152:153], v[60:61]
	v_pk_mul_f32 v[158:159], v[150:151], v[152:153]
	v_pk_mul_f32 v[150:151], v[132:133], v[4:5]
	v_pk_mul_f32 v[152:153], v[144:145], v[36:37]
	v_pk_fma_f32 v[150:151], v[134:135], v[12:13], v[150:151]
	v_pk_fma_f32 v[152:153], v[146:147], v[44:45], v[152:153]
	v_pk_fma_f32 v[150:151], v[136:137], v[20:21], v[150:151]
	v_pk_fma_f32 v[152:153], v[148:149], v[52:53], v[152:153]
	v_pk_add_f32 v[150:151], v[150:151], v[28:29]
	v_pk_add_f32 v[152:153], v[152:153], v[60:61]
	v_pk_mul_f32 v[160:161], v[150:151], v[152:153]
	v_cvt_pk_bf16_f32 v204, v154, v156
	v_cvt_pk_bf16_f32 v205, v158, v160
	v_cvt_pk_bf16_f32 v206, v155, v157
	v_cvt_pk_bf16_f32 v207, v159, v161
	v_lshlrev_b32_e32 v126, 16, v67
	v_and_b32_e32 v127, v232, v67
	v_lshlrev_b32_e32 v138, 16, v97
	v_and_b32_e32 v139, v232, v97
	v_lshlrev_b32_e32 v128, 16, v71
	v_and_b32_e32 v129, v232, v71
	v_lshlrev_b32_e32 v140, 16, v101
	v_and_b32_e32 v141, v232, v101
	v_lshlrev_b32_e32 v130, 16, v75
	v_and_b32_e32 v131, v232, v75
	v_lshlrev_b32_e32 v142, 16, v105
	v_and_b32_e32 v143, v232, v105
	v_lshlrev_b32_e32 v132, 16, v79
	v_and_b32_e32 v133, v232, v79
	v_lshlrev_b32_e32 v144, 16, v109
	v_and_b32_e32 v145, v232, v109
	v_lshlrev_b32_e32 v134, 16, v83
	v_and_b32_e32 v135, v232, v83
	v_lshlrev_b32_e32 v146, 16, v113
	v_and_b32_e32 v147, v232, v113
	v_lshlrev_b32_e32 v136, 16, v87
	v_and_b32_e32 v137, v232, v87
	v_lshlrev_b32_e32 v148, 16, v117
	v_and_b32_e32 v149, v232, v117
	v_pk_mul_f32 v[150:151], v[126:127], v[6:7]
	v_pk_mul_f32 v[152:153], v[138:139], v[38:39]
	v_pk_fma_f32 v[150:151], v[128:129], v[14:15], v[150:151]
	v_pk_fma_f32 v[152:153], v[140:141], v[46:47], v[152:153]
	v_pk_fma_f32 v[150:151], v[130:131], v[22:23], v[150:151]
	v_pk_fma_f32 v[152:153], v[142:143], v[54:55], v[152:153]
	v_pk_add_f32 v[150:151], v[150:151], v[30:31]
	v_pk_add_f32 v[152:153], v[152:153], v[62:63]
	v_pk_mul_f32 v[154:155], v[150:151], v[152:153]
	v_pk_mul_f32 v[150:151], v[128:129], v[6:7]
	v_pk_mul_f32 v[152:153], v[140:141], v[38:39]
	v_pk_fma_f32 v[150:151], v[130:131], v[14:15], v[150:151]
	v_pk_fma_f32 v[152:153], v[142:143], v[46:47], v[152:153]
	v_pk_fma_f32 v[150:151], v[132:133], v[22:23], v[150:151]
	v_pk_fma_f32 v[152:153], v[144:145], v[54:55], v[152:153]
	v_pk_add_f32 v[150:151], v[150:151], v[30:31]
	v_pk_add_f32 v[152:153], v[152:153], v[62:63]
	v_pk_mul_f32 v[156:157], v[150:151], v[152:153]
	v_pk_mul_f32 v[150:151], v[130:131], v[6:7]
	v_pk_mul_f32 v[152:153], v[142:143], v[38:39]
	v_pk_fma_f32 v[150:151], v[132:133], v[14:15], v[150:151]
	v_pk_fma_f32 v[152:153], v[144:145], v[46:47], v[152:153]
	v_pk_fma_f32 v[150:151], v[134:135], v[22:23], v[150:151]
	v_pk_fma_f32 v[152:153], v[146:147], v[54:55], v[152:153]
	v_pk_add_f32 v[150:151], v[150:151], v[30:31]
	v_pk_add_f32 v[152:153], v[152:153], v[62:63]
	v_pk_mul_f32 v[158:159], v[150:151], v[152:153]
	v_pk_mul_f32 v[150:151], v[132:133], v[6:7]
	v_pk_mul_f32 v[152:153], v[144:145], v[38:39]
	v_pk_fma_f32 v[150:151], v[134:135], v[14:15], v[150:151]
	v_pk_fma_f32 v[152:153], v[146:147], v[46:47], v[152:153]
	v_pk_fma_f32 v[150:151], v[136:137], v[22:23], v[150:151]
	v_pk_fma_f32 v[152:153], v[148:149], v[54:55], v[152:153]
	v_pk_add_f32 v[150:151], v[150:151], v[30:31]
	v_pk_add_f32 v[152:153], v[152:153], v[62:63]
	v_pk_mul_f32 v[160:161], v[150:151], v[152:153]
	v_cvt_pk_bf16_f32 v208, v154, v156
	v_cvt_pk_bf16_f32 v209, v158, v160
	v_cvt_pk_bf16_f32 v210, v155, v157
	v_cvt_pk_bf16_f32 v211, v159, v161
	s_add_u32 s14, s14, 1
	s_min_u32 s14, s14, 17
	s_lshr_b32 s0, s2, 4
	s_lshl_b32 s1, s14, 5
	s_add_u32 s0, s0, s1
	s_lshl_b32 s15, s0, 6
	v_readlane_b32 s4, v236, 53
	v_readlane_b32 s5, v236, 54
	s_lshl_b32 s0, s15, 14
	s_add_u32 s4, s4, s0
	s_addc_u32 s5, s5, 0
	s_sub_u32 s4, s4, 0x3000
	s_subb_u32 s5, s5, 0
	s_add_u32 s6, s4, 0x1000
	s_addc_u32 s7, s5, 0
	s_and_b32 s17, s2, 15
	s_lshl_b32 s17, s17, 7
	v_readlane_b32 s18, v235, 35
	v_readlane_b32 s19, v235, 36
	s_cmpk_lt_u32 s15, 0x1000
	s_cbranch_scc0 .Lhp_lat_i2
	s_lshr_b32 s0, s15, 8
	s_lshl_b32 s0, s0, 11
	s_add_u32 s0, s0, s17
	s_lshl_b32 s0, s0, 8
	s_and_b32 s1, s15, 255
	s_add_u32 s0, s0, s1
	s_lshl_b32 s0, s0, 1
	s_cmp_eq_u32 s1, 0
	s_cselect_b32 s22, 1, 0
	s_cmp_eq_u32 s1, 192
	s_cselect_b32 s23, 1, 0
	s_mov_b32 s25, 0
	s_branch .Lhp_latd_i2

.Lhp_latd_i2:
	s_add_u32 s18, s18, s0
	s_addc_u32 s19, s19, 0
	s_cmp_lg_u32 s22, 0
	s_cselect_b64 s[0:1], s[10:11], 0
	v_cndmask_b32_e64 v124, v118, v119, s[0:1]
	s_cmp_lg_u32 s23, 0
	s_cselect_b64 s[0:1], s[12:13], 0
	v_cndmask_b32_e64 v125, v123, v122, s[0:1]
	global_load_dwordx4 v[64:67], v124, s[4:5]
	global_load_dwordx4 v[94:97], v124, s[6:7]
	global_load_dwordx4 v[68:71], v119, s[4:5]
	global_load_dwordx4 v[98:101], v119, s[6:7]
	global_load_dwordx4 v[72:75], v120, s[4:5]
	global_load_dwordx4 v[102:105], v120, s[6:7]
	global_load_dwordx4 v[76:79], v121, s[4:5]
	global_load_dwordx4 v[106:109], v121, s[6:7]
	global_load_dwordx4 v[80:83], v122, s[4:5]
	global_load_dwordx4 v[110:113], v122, s[6:7]
	global_load_dwordx4 v[84:87], v125, s[4:5]
	global_load_dwordx4 v[114:117], v125, s[6:7]
	s_barrier
	ds_write_b64 v212, v[196:197] offset:0
	ds_write_b64 v212, v[198:199] offset:144
	ds_write_b64 v212, v[200:201] offset:288
	ds_write_b64 v212, v[202:203] offset:432
	ds_write_b64 v212, v[204:205] offset:576
	ds_write_b64 v212, v[206:207] offset:720
	ds_write_b64 v212, v[208:209] offset:864
	ds_write_b64 v212, v[210:211] offset:1008
	s_waitcnt lgkmcnt(0)
	s_barrier
	ds_read_b128 v[216:219], v213 offset:0
	ds_read_b128 v[220:223], v213 offset:16
	ds_read_b128 v[224:227], v213 offset:32
	ds_read_b128 v[228:231], v213 offset:48
	s_cmp_lg_u32 s24, 0
	s_cselect_b64 s[0:1], -1, 0
	v_cndmask_b32_e64 v162, v214, v215, s[0:1]
	s_waitcnt lgkmcnt(0)
	global_store_dwordx4 v162, v[216:219], s[8:9] offset:0
	global_store_dwordx4 v162, v[220:223], s[8:9] offset:16
	global_store_dwordx4 v162, v[224:227], s[8:9] offset:32
	global_store_dwordx4 v162, v[228:231], s[8:9] offset:48
	s_add_u32 s16, s16, 1
	s_cmp_lt_u32 s16, 18
	s_cbranch_scc1 .Lhp_item
	s_waitcnt vmcnt(0)
	s_barrier
	s_branch .LBB0_425
